# v41 + nt on ACT stores of the up epilogue
# baseline (speedup 1.0000x reference)
.LBB0_162:
	v_mov_b32_e32 v140, v1
	v_mov_b32_e32 v141, v142
	v_pk_mul_f32 v[124:125], v[128:129], v[124:125]
	v_add_u32_e32 v145, s43, v140
	v_lshl_add_u32 v146, v145, 2, 0
	v_add_u32_e32 v146, 0x20400, v146
	ds_read_b32 v147, v146
	v_pk_mul_f32 v[122:123], v[126:127], v[122:123]
	v_pk_mul_f32 v[116:117], v[120:121], v[116:117]
	v_pk_mul_f32 v[114:115], v[118:119], v[114:115]
	s_lshl_b32 s0, s20, 8
	s_waitcnt lgkmcnt(0)
	v_mul_f32_e32 v148, 0xbfb8aa3b, v147
	v_pk_mul_f32 v[128:129], v[128:129], v[148:149] op_sel_hi:[1,0]
	v_pk_mul_f32 v[126:127], v[126:127], v[148:149] op_sel_hi:[1,0]
	v_pk_mul_f32 v[120:121], v[120:121], v[148:149] op_sel_hi:[1,0]
	v_exp_f32_e32 v126, v126
	v_exp_f32_e32 v127, v127
	v_exp_f32_e32 v128, v128
	v_exp_f32_e32 v129, v129
	v_pk_mul_f32 v[118:119], v[118:119], v[148:149] op_sel_hi:[1,0]
	v_exp_f32_e32 v120, v120
	v_exp_f32_e32 v121, v121
	v_exp_f32_e32 v118, v118
	v_exp_f32_e32 v119, v119
	v_pk_add_f32 v[128:129], v[128:129], 1.0 op_sel_hi:[1,0]
	v_pk_add_f32 v[126:127], v[126:127], 1.0 op_sel_hi:[1,0]
	v_pk_add_f32 v[120:121], v[120:121], 1.0 op_sel_hi:[1,0]
	s_mul_i32 s1, s20, 0x2c0000
	v_rcp_f32_e32 v126, v126
	v_rcp_f32_e32 v127, v127
	v_rcp_f32_e32 v128, v128
	v_rcp_f32_e32 v129, v129
	v_pk_add_f32 v[118:119], v[118:119], 1.0 op_sel_hi:[1,0]
	v_rcp_f32_e32 v120, v120
	v_rcp_f32_e32 v121, v121
	s_mul_hi_i32 s0, s0, 0x2c00
	s_add_u32 s1, s41, s1
	v_rcp_f32_e32 v118, v118
	v_rcp_f32_e32 v119, v119
	s_addc_u32 s0, s42, s0
	s_lshl_b32 s20, s21, 7
	s_ashr_i32 s21, s20, 31
	v_mul_f32_e32 v150, v147, v147
	s_lshl_b64 s[20:21], s[20:21], 1
	v_pk_mul_f32 v[128:129], v[150:151], v[128:129] op_sel_hi:[0,1]
	v_pk_mul_f32 v[126:127], v[150:151], v[126:127] op_sel_hi:[0,1]
	v_pk_mul_f32 v[120:121], v[150:151], v[120:121] op_sel_hi:[0,1]
	s_add_u32 s1, s1, s20
	v_pk_mul_f32 v[124:125], v[124:125], v[128:129]
	v_pk_mul_f32 v[122:123], v[122:123], v[126:127]
	v_pk_mul_f32 v[118:119], v[150:151], v[118:119] op_sel_hi:[0,1]
	v_pk_mul_f32 v[116:117], v[116:117], v[120:121]
	s_addc_u32 s0, s0, s21
	v_cvt_pk_bf16_f32 v122, v122, v123
	v_cvt_pk_bf16_f32 v123, v124, v125
	v_pk_mul_f32 v[114:115], v[114:115], v[118:119]
	s_add_u32 s20, s1, s45
	v_cvt_pk_bf16_f32 v124, v114, v115
	v_cvt_pk_bf16_f32 v125, v116, v117
	ds_read_b32 v116, v146 offset:64
	v_lshlrev_b32_e32 v140, 3, v141
	s_addc_u32 s21, s0, 0
	v_ashrrev_i32_e32 v141, 31, v140
	v_lshl_add_u64 v[140:141], v[140:141], 1, s[20:21]
	s_movk_i32 s0, 0x2c00
	v_mad_i64_i32 v[114:115], s[20:21], v145, s0, v[140:141]
	global_store_dwordx4 v[114:115], v[122:125], off nt
	v_add_u32_e32 v115, 16, v145
	s_waitcnt lgkmcnt(0)
	v_mul_f32_e32 v114, 0xbfb8aa3b, v116
	v_pk_mul_f32 v[108:109], v[112:113], v[108:109]
	v_pk_mul_f32 v[106:107], v[110:111], v[106:107]
	v_pk_mul_f32 v[112:113], v[112:113], v[114:115] op_sel_hi:[1,0]
	v_pk_mul_f32 v[110:111], v[110:111], v[114:115] op_sel_hi:[1,0]
	v_pk_mul_f32 v[100:101], v[104:105], v[100:101]
	v_pk_mul_f32 v[104:105], v[104:105], v[114:115] op_sel_hi:[1,0]
	v_exp_f32_e32 v110, v110
	v_exp_f32_e32 v111, v111
	v_exp_f32_e32 v112, v112
	v_exp_f32_e32 v113, v113
	v_pk_mul_f32 v[98:99], v[102:103], v[98:99]
	v_pk_mul_f32 v[102:103], v[102:103], v[114:115] op_sel_hi:[1,0]
	v_exp_f32_e32 v104, v104
	v_exp_f32_e32 v105, v105
	v_exp_f32_e32 v102, v102
	v_exp_f32_e32 v103, v103
	v_pk_add_f32 v[112:113], v[112:113], 1.0 op_sel_hi:[1,0]
	v_pk_add_f32 v[110:111], v[110:111], 1.0 op_sel_hi:[1,0]
	v_pk_add_f32 v[104:105], v[104:105], 1.0 op_sel_hi:[1,0]
	v_rcp_f32_e32 v110, v110
	v_rcp_f32_e32 v111, v111
	v_rcp_f32_e32 v112, v112
	v_rcp_f32_e32 v113, v113
	v_pk_add_f32 v[102:103], v[102:103], 1.0 op_sel_hi:[1,0]
	v_rcp_f32_e32 v104, v104
	v_rcp_f32_e32 v105, v105
	v_rcp_f32_e32 v102, v102
	v_rcp_f32_e32 v103, v103
	v_mul_f32_e32 v116, v116, v116
	v_pk_mul_f32 v[112:113], v[116:117], v[112:113] op_sel_hi:[0,1]
	v_pk_mul_f32 v[110:111], v[116:117], v[110:111] op_sel_hi:[0,1]
	v_pk_mul_f32 v[104:105], v[116:117], v[104:105] op_sel_hi:[0,1]
	v_pk_mul_f32 v[108:109], v[108:109], v[112:113]
	v_pk_mul_f32 v[106:107], v[106:107], v[110:111]
	v_pk_mul_f32 v[102:103], v[116:117], v[102:103] op_sel_hi:[0,1]
	v_pk_mul_f32 v[100:101], v[100:101], v[104:105]
	v_cvt_pk_bf16_f32 v106, v106, v107
	v_cvt_pk_bf16_f32 v107, v108, v109
	v_pk_mul_f32 v[98:99], v[98:99], v[102:103]
	v_pk_mul_f32 v[92:93], v[96:97], v[92:93]
	v_cvt_pk_bf16_f32 v108, v98, v99
	v_cvt_pk_bf16_f32 v109, v100, v101
	ds_read_b32 v100, v146 offset:128
	v_mad_i64_i32 v[98:99], s[20:21], v115, s0, v[140:141]
	global_store_dwordx4 v[98:99], v[106:109], off nt
	v_add_u32_e32 v99, 32, v145
	s_waitcnt lgkmcnt(0)
	v_mul_f32_e32 v98, 0xbfb8aa3b, v100
	v_pk_mul_f32 v[90:91], v[94:95], v[90:91]
	v_pk_mul_f32 v[96:97], v[96:97], v[98:99] op_sel_hi:[1,0]
	v_pk_mul_f32 v[94:95], v[94:95], v[98:99] op_sel_hi:[1,0]
	v_pk_mul_f32 v[84:85], v[88:89], v[84:85]
	v_pk_mul_f32 v[88:89], v[88:89], v[98:99] op_sel_hi:[1,0]
	v_exp_f32_e32 v94, v94
	v_exp_f32_e32 v95, v95
	v_exp_f32_e32 v96, v96
	v_exp_f32_e32 v97, v97
	v_pk_mul_f32 v[82:83], v[86:87], v[82:83]
	v_pk_mul_f32 v[86:87], v[86:87], v[98:99] op_sel_hi:[1,0]
	v_exp_f32_e32 v88, v88
	v_exp_f32_e32 v89, v89
	v_exp_f32_e32 v86, v86
	v_exp_f32_e32 v87, v87
	v_pk_add_f32 v[96:97], v[96:97], 1.0 op_sel_hi:[1,0]
	v_pk_add_f32 v[94:95], v[94:95], 1.0 op_sel_hi:[1,0]
	v_pk_add_f32 v[88:89], v[88:89], 1.0 op_sel_hi:[1,0]
	v_rcp_f32_e32 v94, v94
	v_rcp_f32_e32 v95, v95
	v_rcp_f32_e32 v96, v96
	v_rcp_f32_e32 v97, v97
	v_pk_add_f32 v[86:87], v[86:87], 1.0 op_sel_hi:[1,0]
	v_rcp_f32_e32 v88, v88
	v_rcp_f32_e32 v89, v89
	v_rcp_f32_e32 v86, v86
	v_rcp_f32_e32 v87, v87
	v_mul_f32_e32 v100, v100, v100
	v_pk_mul_f32 v[96:97], v[100:101], v[96:97] op_sel_hi:[0,1]
	v_pk_mul_f32 v[94:95], v[100:101], v[94:95] op_sel_hi:[0,1]
	v_pk_mul_f32 v[88:89], v[100:101], v[88:89] op_sel_hi:[0,1]
	v_pk_mul_f32 v[92:93], v[92:93], v[96:97]
	v_pk_mul_f32 v[90:91], v[90:91], v[94:95]
	v_pk_mul_f32 v[86:87], v[100:101], v[86:87] op_sel_hi:[0,1]
	v_pk_mul_f32 v[84:85], v[84:85], v[88:89]
	v_cvt_pk_bf16_f32 v90, v90, v91
	v_cvt_pk_bf16_f32 v91, v92, v93
	v_pk_mul_f32 v[82:83], v[82:83], v[86:87]
	v_pk_mul_f32 v[76:77], v[80:81], v[76:77]
	v_cvt_pk_bf16_f32 v92, v82, v83
	v_cvt_pk_bf16_f32 v93, v84, v85
	ds_read_b32 v84, v146 offset:192
	v_mad_i64_i32 v[82:83], s[20:21], v99, s0, v[140:141]
	global_store_dwordx4 v[82:83], v[90:93], off nt
	v_add_u32_e32 v83, 48, v145
	s_waitcnt lgkmcnt(0)
	v_mul_f32_e32 v82, 0xbfb8aa3b, v84
	v_pk_mul_f32 v[74:75], v[78:79], v[74:75]
	v_pk_mul_f32 v[80:81], v[80:81], v[82:83] op_sel_hi:[1,0]
	v_pk_mul_f32 v[78:79], v[78:79], v[82:83] op_sel_hi:[1,0]
	v_pk_mul_f32 v[68:69], v[72:73], v[68:69]
	v_pk_mul_f32 v[72:73], v[72:73], v[82:83] op_sel_hi:[1,0]
	v_exp_f32_e32 v78, v78
	v_exp_f32_e32 v79, v79
	v_exp_f32_e32 v80, v80
	v_exp_f32_e32 v81, v81
	v_pk_mul_f32 v[66:67], v[70:71], v[66:67]
	v_pk_mul_f32 v[70:71], v[70:71], v[82:83] op_sel_hi:[1,0]
	v_exp_f32_e32 v72, v72
	v_exp_f32_e32 v73, v73
	v_exp_f32_e32 v70, v70
	v_exp_f32_e32 v71, v71
	v_pk_add_f32 v[80:81], v[80:81], 1.0 op_sel_hi:[1,0]
	v_pk_add_f32 v[78:79], v[78:79], 1.0 op_sel_hi:[1,0]
	v_pk_add_f32 v[72:73], v[72:73], 1.0 op_sel_hi:[1,0]
	v_rcp_f32_e32 v78, v78
	v_rcp_f32_e32 v79, v79
	v_rcp_f32_e32 v80, v80
	v_rcp_f32_e32 v81, v81
	v_pk_add_f32 v[70:71], v[70:71], 1.0 op_sel_hi:[1,0]
	v_rcp_f32_e32 v72, v72
	v_rcp_f32_e32 v73, v73
	v_rcp_f32_e32 v70, v70
	v_rcp_f32_e32 v71, v71
	v_mul_f32_e32 v84, v84, v84
	v_pk_mul_f32 v[80:81], v[84:85], v[80:81] op_sel_hi:[0,1]
	v_pk_mul_f32 v[78:79], v[84:85], v[78:79] op_sel_hi:[0,1]
	v_pk_mul_f32 v[72:73], v[84:85], v[72:73] op_sel_hi:[0,1]
	v_pk_mul_f32 v[76:77], v[76:77], v[80:81]
	v_pk_mul_f32 v[74:75], v[74:75], v[78:79]
	v_pk_mul_f32 v[70:71], v[84:85], v[70:71] op_sel_hi:[0,1]
	v_pk_mul_f32 v[68:69], v[68:69], v[72:73]
	v_cvt_pk_bf16_f32 v74, v74, v75
	v_cvt_pk_bf16_f32 v75, v76, v77
	v_pk_mul_f32 v[66:67], v[66:67], v[70:71]
	v_pk_mul_f32 v[60:61], v[64:65], v[60:61]
	v_cvt_pk_bf16_f32 v76, v66, v67
	v_cvt_pk_bf16_f32 v77, v68, v69
	ds_read_b32 v68, v146 offset:512
	v_mad_i64_i32 v[66:67], s[20:21], v83, s0, v[140:141]
	global_store_dwordx4 v[66:67], v[74:77], off nt
	v_add_u32_e32 v67, 0x80, v145
	s_waitcnt lgkmcnt(0)
	v_mul_f32_e32 v66, 0xbfb8aa3b, v68
	v_pk_mul_f32 v[58:59], v[62:63], v[58:59]
	v_pk_mul_f32 v[64:65], v[64:65], v[66:67] op_sel_hi:[1,0]
	v_pk_mul_f32 v[62:63], v[62:63], v[66:67] op_sel_hi:[1,0]
	v_pk_mul_f32 v[52:53], v[56:57], v[52:53]
	v_pk_mul_f32 v[56:57], v[56:57], v[66:67] op_sel_hi:[1,0]
	v_exp_f32_e32 v62, v62
	v_exp_f32_e32 v63, v63
	v_exp_f32_e32 v64, v64
	v_exp_f32_e32 v65, v65
	v_pk_mul_f32 v[50:51], v[54:55], v[50:51]
	v_pk_mul_f32 v[54:55], v[54:55], v[66:67] op_sel_hi:[1,0]
	v_exp_f32_e32 v56, v56
	v_exp_f32_e32 v57, v57
	v_exp_f32_e32 v54, v54
	v_exp_f32_e32 v55, v55
	v_pk_add_f32 v[64:65], v[64:65], 1.0 op_sel_hi:[1,0]
	v_pk_add_f32 v[62:63], v[62:63], 1.0 op_sel_hi:[1,0]
	v_pk_add_f32 v[56:57], v[56:57], 1.0 op_sel_hi:[1,0]
	v_rcp_f32_e32 v62, v62
	v_rcp_f32_e32 v63, v63
	v_rcp_f32_e32 v64, v64
	v_rcp_f32_e32 v65, v65
	v_pk_add_f32 v[54:55], v[54:55], 1.0 op_sel_hi:[1,0]
	v_rcp_f32_e32 v56, v56
	v_rcp_f32_e32 v57, v57
	v_rcp_f32_e32 v54, v54
	v_rcp_f32_e32 v55, v55
	v_mul_f32_e32 v68, v68, v68
	v_pk_mul_f32 v[64:65], v[68:69], v[64:65] op_sel_hi:[0,1]
	v_pk_mul_f32 v[62:63], v[68:69], v[62:63] op_sel_hi:[0,1]
	v_pk_mul_f32 v[56:57], v[68:69], v[56:57] op_sel_hi:[0,1]
	v_pk_mul_f32 v[60:61], v[60:61], v[64:65]
	v_pk_mul_f32 v[58:59], v[58:59], v[62:63]
	v_pk_mul_f32 v[54:55], v[68:69], v[54:55] op_sel_hi:[0,1]
	v_pk_mul_f32 v[52:53], v[52:53], v[56:57]
	v_cvt_pk_bf16_f32 v58, v58, v59
	v_cvt_pk_bf16_f32 v59, v60, v61
	v_pk_mul_f32 v[50:51], v[50:51], v[54:55]
	v_pk_mul_f32 v[44:45], v[48:49], v[44:45]
	v_cvt_pk_bf16_f32 v60, v50, v51
	v_cvt_pk_bf16_f32 v61, v52, v53
	ds_read_b32 v52, v146 offset:576
	v_mad_i64_i32 v[50:51], s[20:21], v67, s0, v[140:141]
	global_store_dwordx4 v[50:51], v[58:61], off nt
	v_add_u32_e32 v51, 0x90, v145
	s_waitcnt lgkmcnt(0)
	v_mul_f32_e32 v50, 0xbfb8aa3b, v52
	v_pk_mul_f32 v[42:43], v[46:47], v[42:43]
	v_pk_mul_f32 v[48:49], v[48:49], v[50:51] op_sel_hi:[1,0]
	v_pk_mul_f32 v[46:47], v[46:47], v[50:51] op_sel_hi:[1,0]
	v_pk_mul_f32 v[36:37], v[40:41], v[36:37]
	v_pk_mul_f32 v[40:41], v[40:41], v[50:51] op_sel_hi:[1,0]
	v_exp_f32_e32 v46, v46
	v_exp_f32_e32 v47, v47
	v_exp_f32_e32 v48, v48
	v_exp_f32_e32 v49, v49
	v_pk_mul_f32 v[34:35], v[38:39], v[34:35]
	v_pk_mul_f32 v[38:39], v[38:39], v[50:51] op_sel_hi:[1,0]
	v_exp_f32_e32 v40, v40
	v_exp_f32_e32 v41, v41
	v_exp_f32_e32 v38, v38
	v_exp_f32_e32 v39, v39
	v_pk_add_f32 v[48:49], v[48:49], 1.0 op_sel_hi:[1,0]
	v_pk_add_f32 v[46:47], v[46:47], 1.0 op_sel_hi:[1,0]
	v_pk_add_f32 v[40:41], v[40:41], 1.0 op_sel_hi:[1,0]
	v_rcp_f32_e32 v46, v46
	v_rcp_f32_e32 v47, v47
	v_rcp_f32_e32 v48, v48
	v_rcp_f32_e32 v49, v49
	v_pk_add_f32 v[38:39], v[38:39], 1.0 op_sel_hi:[1,0]
	v_rcp_f32_e32 v40, v40
	v_rcp_f32_e32 v41, v41
	v_rcp_f32_e32 v38, v38
	v_rcp_f32_e32 v39, v39
	v_mul_f32_e32 v52, v52, v52
	v_pk_mul_f32 v[48:49], v[52:53], v[48:49] op_sel_hi:[0,1]
	v_pk_mul_f32 v[46:47], v[52:53], v[46:47] op_sel_hi:[0,1]
	v_pk_mul_f32 v[40:41], v[52:53], v[40:41] op_sel_hi:[0,1]
	v_pk_mul_f32 v[44:45], v[44:45], v[48:49]
	v_pk_mul_f32 v[42:43], v[42:43], v[46:47]
	v_pk_mul_f32 v[38:39], v[52:53], v[38:39] op_sel_hi:[0,1]
	v_pk_mul_f32 v[36:37], v[36:37], v[40:41]
	v_cvt_pk_bf16_f32 v42, v42, v43
	v_cvt_pk_bf16_f32 v43, v44, v45
	v_pk_mul_f32 v[34:35], v[34:35], v[38:39]
	v_pk_mul_f32 v[28:29], v[32:33], v[28:29]
	v_cvt_pk_bf16_f32 v44, v34, v35
	v_cvt_pk_bf16_f32 v45, v36, v37
	ds_read_b32 v36, v146 offset:640
	v_mad_i64_i32 v[34:35], s[20:21], v51, s0, v[140:141]
	global_store_dwordx4 v[34:35], v[42:45], off nt
	v_add_u32_e32 v35, 0xa0, v145
	s_waitcnt lgkmcnt(0)
	v_mul_f32_e32 v34, 0xbfb8aa3b, v36
	v_pk_mul_f32 v[26:27], v[30:31], v[26:27]
	v_pk_mul_f32 v[32:33], v[32:33], v[34:35] op_sel_hi:[1,0]
	v_pk_mul_f32 v[30:31], v[30:31], v[34:35] op_sel_hi:[1,0]
	v_pk_mul_f32 v[20:21], v[24:25], v[20:21]
	v_pk_mul_f32 v[24:25], v[24:25], v[34:35] op_sel_hi:[1,0]
	v_exp_f32_e32 v30, v30
	v_exp_f32_e32 v31, v31
	v_exp_f32_e32 v32, v32
	v_exp_f32_e32 v33, v33
	v_pk_mul_f32 v[18:19], v[22:23], v[18:19]
	v_pk_mul_f32 v[22:23], v[22:23], v[34:35] op_sel_hi:[1,0]
	v_exp_f32_e32 v24, v24
	v_exp_f32_e32 v25, v25
	v_exp_f32_e32 v22, v22
	v_exp_f32_e32 v23, v23
	v_pk_add_f32 v[32:33], v[32:33], 1.0 op_sel_hi:[1,0]
	v_pk_add_f32 v[30:31], v[30:31], 1.0 op_sel_hi:[1,0]
	v_pk_add_f32 v[24:25], v[24:25], 1.0 op_sel_hi:[1,0]
	v_rcp_f32_e32 v30, v30
	v_rcp_f32_e32 v31, v31
	v_rcp_f32_e32 v32, v32
	v_rcp_f32_e32 v33, v33
	v_pk_add_f32 v[22:23], v[22:23], 1.0 op_sel_hi:[1,0]
	v_rcp_f32_e32 v24, v24
	v_rcp_f32_e32 v25, v25
	v_rcp_f32_e32 v22, v22
	v_rcp_f32_e32 v23, v23
	v_mul_f32_e32 v36, v36, v36
	v_pk_mul_f32 v[32:33], v[36:37], v[32:33] op_sel_hi:[0,1]
	v_pk_mul_f32 v[30:31], v[36:37], v[30:31] op_sel_hi:[0,1]
	v_pk_mul_f32 v[24:25], v[36:37], v[24:25] op_sel_hi:[0,1]
	v_pk_mul_f32 v[28:29], v[28:29], v[32:33]
	v_pk_mul_f32 v[26:27], v[26:27], v[30:31]
	v_pk_mul_f32 v[22:23], v[36:37], v[22:23] op_sel_hi:[0,1]
	v_pk_mul_f32 v[20:21], v[20:21], v[24:25]
	v_cvt_pk_bf16_f32 v26, v26, v27
	v_cvt_pk_bf16_f32 v27, v28, v29
	v_pk_mul_f32 v[18:19], v[18:19], v[22:23]
	v_pk_mul_f32 v[12:13], v[16:17], v[12:13]
	v_cvt_pk_bf16_f32 v28, v18, v19
	v_cvt_pk_bf16_f32 v29, v20, v21
	ds_read_b32 v20, v146 offset:704
	v_mad_i64_i32 v[18:19], s[20:21], v35, s0, v[140:141]
	global_store_dwordx4 v[18:19], v[26:29], off nt
	v_add_u32_e32 v19, 0xb0, v145
	s_waitcnt lgkmcnt(0)
	v_mul_f32_e32 v18, 0xbfb8aa3b, v20
	v_pk_mul_f32 v[10:11], v[14:15], v[10:11]
	v_pk_mul_f32 v[16:17], v[16:17], v[18:19] op_sel_hi:[1,0]
	v_pk_mul_f32 v[14:15], v[14:15], v[18:19] op_sel_hi:[1,0]
	v_pk_mul_f32 v[2:3], v[6:7], v[2:3]
	v_pk_mul_f32 v[6:7], v[6:7], v[18:19] op_sel_hi:[1,0]
	v_exp_f32_e32 v14, v14
	v_exp_f32_e32 v15, v15
	v_exp_f32_e32 v16, v16
	v_exp_f32_e32 v17, v17
	v_exp_f32_e32 v6, v6
	v_exp_f32_e32 v7, v7
	v_pk_mul_f32 v[4:5], v[8:9], v[4:5]
	v_pk_mul_f32 v[8:9], v[8:9], v[18:19] op_sel_hi:[1,0]
	v_pk_add_f32 v[16:17], v[16:17], 1.0 op_sel_hi:[1,0]
	v_exp_f32_e32 v8, v8
	v_exp_f32_e32 v9, v9
	v_pk_add_f32 v[14:15], v[14:15], 1.0 op_sel_hi:[1,0]
	v_pk_add_f32 v[6:7], v[6:7], 1.0 op_sel_hi:[1,0]
	v_rcp_f32_e32 v14, v14
	v_rcp_f32_e32 v15, v15
	v_rcp_f32_e32 v16, v16
	v_rcp_f32_e32 v17, v17
	v_rcp_f32_e32 v6, v6
	v_rcp_f32_e32 v7, v7
	v_pk_add_f32 v[8:9], v[8:9], 1.0 op_sel_hi:[1,0]
	v_mul_f32_e32 v20, v20, v20
	v_rcp_f32_e32 v8, v8
	v_rcp_f32_e32 v9, v9
	v_pk_mul_f32 v[16:17], v[20:21], v[16:17] op_sel_hi:[0,1]
	v_pk_mul_f32 v[14:15], v[20:21], v[14:15] op_sel_hi:[0,1]
	v_pk_mul_f32 v[6:7], v[20:21], v[6:7] op_sel_hi:[0,1]
	v_pk_mul_f32 v[12:13], v[12:13], v[16:17]
	v_pk_mul_f32 v[10:11], v[10:11], v[14:15]
	v_pk_mul_f32 v[2:3], v[2:3], v[6:7]
	v_cvt_pk_bf16_f32 v10, v10, v11
	v_cvt_pk_bf16_f32 v11, v12, v13
	v_pk_mul_f32 v[8:9], v[20:21], v[8:9] op_sel_hi:[0,1]
	v_cvt_pk_bf16_f32 v12, v2, v3
	v_mad_i64_i32 v[2:3], s[20:21], v19, s0, v[140:141]
	s_mov_b64 s[20:21], -1
	s_andn2_b64 vcc, exec, s[4:5]
	v_pk_mul_f32 v[4:5], v[4:5], v[8:9]
	s_nop 0
	v_cvt_pk_bf16_f32 v13, v4, v5
	global_store_dwordx4 v[2:3], v[10:13], off nt
	s_cbranch_vccnz .LBB0_155
	s_andn2_b64 vcc, exec, s[8:9]
	s_cbranch_vccnz .LBB0_154
	s_barrier
	s_branch .LBB0_154
